# prologue de-serialisation: all seven GEMM prologue stage loads issued before the first wait (counted vmcnt 8 then 6)
# baseline (speedup 1.0000x reference)
.LBB0_66:
	s_lshl_b32 s59, s24, 6
	s_lshl_b32 s30, s24, 13
	s_lshl_b32 s24, s25, 5
	s_and_b32 s36, s24, 0x60
	s_add_i32 m0, s43, 0x18000
	v_lshl_add_u64 v[10:11], v[10:11], 0, s[22:23]
	s_lshl_b32 s31, s36, 7
	global_load_lds_dwordx4 v[10:11], off
	v_lshl_add_u64 v[8:9], v[8:9], 0, s[22:23]
	s_add_i32 m0, s43, 0x1a000
	s_add_i32 s60, s43, 0x8000
	s_add_i32 s61, s43, 0xa000
	global_load_lds_dwordx4 v[8:9], off
	v_lshl_add_u64 v[4:5], v[4:5], 0, s[22:23]
	s_mov_b32 m0, s60
	s_add_u32 s24, s16, 0x40080
	global_load_lds_dwordx4 v[4:5], off
	v_lshl_add_u64 v[4:5], v[6:7], 0, s[22:23]
	s_mov_b32 m0, s61
	s_addc_u32 s25, s17, 0
	global_load_lds_dwordx4 v[4:5], off
	s_add_i32 m0, s43, 0x1c000
	v_lshl_add_u64 v[4:5], s[24:25], 0, v[132:133]
	global_load_lds_dwordx4 v[4:5], off
	v_lshl_add_u64 v[4:5], s[24:25], 0, v[136:137]
	s_add_i32 m0, s43, 0x1e000
	s_cmpk_lt_u32 s21, 0x100
	global_load_lds_dwordx4 v[4:5], off
	v_lshrrev_b32_e32 v4, 1, v2
	v_and_b32_e32 v4, 24, v4
	v_and_b32_e32 v156, 15, v2
	v_lshlrev_b32_e32 v5, 1, v4
	v_lshlrev_b32_e32 v2, 2, v2
	s_cselect_b64 s[24:25], -1, 0
	s_lshl_b32 s62, s20, 4
	s_lshl_b32 s63, s20, 3
	v_lshl_or_b32 v5, v156, 6, v5
	v_and_b32_e32 v2, 32, v2
	s_cmp_lg_u32 s28, 0
	v_bitop3_b32 v6, v5, s30, v2 bitop3:0xde
	v_bitop3_b32 v157, v5, s31, v2 bitop3:0xde
	s_cselect_b64 s[30:31], -1, 0
	s_abs_i32 s64, s63
	v_cvt_f32_u32_e32 v2, s64
	v_or_b32_e32 v158, s36, v4
	v_cvt_f32_u32_e32 v4, s28
	s_bfe_i32 s66, s20, 0x1001c
	v_rcp_iflag_f32_e32 v2, v2
	s_sub_i32 s20, 0, s64
	v_rcp_iflag_f32_e32 v4, v4
	s_waitcnt vmcnt(8)
	s_barrier
	s_waitcnt vmcnt(6)
	v_mul_f32_e32 v2, 0x4f7ffffe, v2
	v_cvt_u32_f32_e32 v2, v2
	v_or_b32_e32 v159, 0xfffffe00, v158
	s_mov_b32 s65, 0
	v_mov_b32_e32 v139, v3
	v_readfirstlane_b32 s21, v2
	v_mul_f32_e32 v2, 0x4f7ffffe, v4
	v_cvt_u32_f32_e32 v2, v2
	s_mul_i32 s20, s20, s21
	s_mul_hi_u32 s20, s21, s20
	s_add_i32 s67, s21, s20
	v_readfirstlane_b32 s21, v2
	v_lshlrev_b32_e32 v2, 14, v12
	v_and_b32_e32 v2, 0xffff8000, v2
	v_lshl_add_u32 v2, v13, 11, v2
	v_and_b32_e32 v4, 1, v12
	v_lshl_or_b32 v2, v4, 6, v2
	v_lshl_add_u32 v138, v14, 1, v2
	v_lshlrev_b32_e32 v2, 14, v15
	s_sub_i32 s20, 0, s28
	v_and_b32_e32 v2, 0xffff8000, v2
	s_mul_i32 s20, s20, s21
	v_lshl_add_u32 v2, v16, 11, v2
	v_and_b32_e32 v4, 1, v15
	s_mul_hi_u32 s20, s21, s20
	v_lshl_or_b32 v2, v4, 6, v2
	s_add_i32 s68, s21, s20
	v_lshl_add_u32 v140, v17, 1, v2
	v_mov_b32_e32 v141, v3
	v_add_u32_e32 v160, 0, v6
	v_mov_b64_e32 v[142:143], s[18:19]
	s_barrier
	s_branch .LBB0_69

.LBB0_346:
	v_and_b32_e32 v193, 15, v180
	v_and_b32_e32 v18, 48, v180
	v_lshlrev_b32_e32 v19, 2, v180
	s_and_b32 s5, s24, 3
	s_lshl_b32 s14, s21, 13
	v_lshl_or_b32 v18, v193, 6, v18
	v_and_b32_e32 v19, 32, v19
	s_add_i32 m0, s37, 0x18000
	v_lshl_add_u64 v[10:11], v[10:11], 0, s[22:23]
	v_bitop3_b32 v20, v18, s14, v19 bitop3:0xde
	s_lshl_b32 s14, s5, 12
	global_load_lds_dwordx4 v[10:11], off
	v_lshl_add_u64 v[8:9], v[8:9], 0, s[22:23]
	s_add_i32 m0, s37, 0x1a000
	s_add_i32 s41, s37, 0x8000
	s_add_i32 s54, s37, 0xa000
	v_bitop3_b32 v92, v18, s14, v19 bitop3:0xde
	global_load_lds_dwordx4 v[8:9], off
	v_lshl_add_u64 v[6:7], v[6:7], 0, s[22:23]
	s_mov_b32 m0, s41
	s_add_u32 s14, s0, 0x40080
	global_load_lds_dwordx4 v[6:7], off
	v_lshl_add_u64 v[4:5], v[4:5], 0, s[22:23]
	s_mov_b32 m0, s54
	s_addc_u32 s15, s1, 0
	global_load_lds_dwordx4 v[4:5], off
	s_add_i32 m0, s37, 0x1c000
	v_lshl_add_u64 v[4:5], s[14:15], 0, v[2:3]
	global_load_lds_dwordx4 v[4:5], off
	v_lshl_add_u64 v[4:5], s[14:15], 0, v[86:87]
	s_add_i32 m0, s37, 0x1e000
	s_add_u32 s10, s10, s12
	global_load_lds_dwordx4 v[4:5], off
	v_lshlrev_b32_e32 v4, 14, v12
	v_and_b32_e32 v4, 0xffff8000, v4
	s_addc_u32 s11, s11, s13
	v_lshl_add_u32 v4, v13, 11, v4
	v_and_b32_e32 v5, 1, v12
	v_lshl_or_b32 v4, v5, 6, v4
	s_add_u32 s10, s17, s10
	v_lshl_add_u32 v4, v14, 1, v4
	v_mov_b32_e32 v5, v3
	s_addc_u32 s11, s20, s11
	v_lshl_add_u64 v[88:89], s[10:11], 0, v[4:5]
	v_lshlrev_b32_e32 v4, 14, v15
	v_and_b32_e32 v4, 0xffff8000, v4
	v_lshl_add_u32 v4, v16, 11, v4
	v_and_b32_e32 v5, 1, v15
	v_lshl_or_b32 v4, v5, 6, v4
	s_waitcnt vmcnt(8)
	s_barrier
	s_waitcnt vmcnt(6)
	v_lshl_add_u32 v4, v17, 1, v4
	v_mov_b32_e32 v5, v3
	v_lshl_add_u64 v[90:91], s[10:11], 0, v[4:5]
	v_mov_b32_e32 v4, 0
	v_lshl_or_b32 v229, s21, 6, v193
	s_mov_b32 s55, -2
	s_mov_b64 s[10:11], 0x100
	v_add_u32_e32 v93, 0, v20
	v_mov_b32_e32 v5, v4
	v_mov_b32_e32 v6, v4
	v_mov_b32_e32 v7, v4
	v_mov_b32_e32 v8, v4
	v_mov_b32_e32 v9, v4
	v_mov_b32_e32 v10, v4
	v_mov_b32_e32 v11, v4
	v_mov_b32_e32 v20, v4
	v_mov_b32_e32 v21, v4
	v_mov_b32_e32 v22, v4
	v_mov_b32_e32 v23, v4
	v_mov_b32_e32 v24, v4
	v_mov_b32_e32 v25, v4
	v_mov_b32_e32 v26, v4
	v_mov_b32_e32 v27, v4
	v_mov_b32_e32 v36, v4
	v_mov_b32_e32 v37, v4
	v_mov_b32_e32 v38, v4
	v_mov_b32_e32 v39, v4
	v_mov_b32_e32 v40, v4
	v_mov_b32_e32 v41, v4
	v_mov_b32_e32 v42, v4
	v_mov_b32_e32 v43, v4
	v_mov_b32_e32 v52, v4
	v_mov_b32_e32 v53, v4
	v_mov_b32_e32 v54, v4
	v_mov_b32_e32 v55, v4
	v_mov_b32_e32 v56, v4
	v_mov_b32_e32 v57, v4
	v_mov_b32_e32 v58, v4
	v_mov_b32_e32 v59, v4
	v_mov_b32_e32 v12, v4
	v_mov_b32_e32 v13, v4
	v_mov_b32_e32 v14, v4
	v_mov_b32_e32 v15, v4
	v_mov_b32_e32 v16, v4
	v_mov_b32_e32 v17, v4
	v_mov_b32_e32 v18, v4
	v_mov_b32_e32 v19, v4
	v_mov_b32_e32 v28, v4
	v_mov_b32_e32 v29, v4
	v_mov_b32_e32 v30, v4
	v_mov_b32_e32 v31, v4
	v_mov_b32_e32 v32, v4
	v_mov_b32_e32 v33, v4
	v_mov_b32_e32 v34, v4
	v_mov_b32_e32 v35, v4
	v_mov_b32_e32 v44, v4
	v_mov_b32_e32 v45, v4
	v_mov_b32_e32 v46, v4
	v_mov_b32_e32 v47, v4
	v_mov_b32_e32 v48, v4
	v_mov_b32_e32 v49, v4
	v_mov_b32_e32 v50, v4
	v_mov_b32_e32 v51, v4
	v_mov_b32_e32 v60, v4
	v_mov_b32_e32 v61, v4
	v_mov_b32_e32 v62, v4
	v_mov_b32_e32 v63, v4
	v_mov_b32_e32 v64, v4
	v_mov_b32_e32 v65, v4
	v_mov_b32_e32 v66, v4
	v_mov_b32_e32 v67, v4
	v_mov_b32_e32 v68, v4
	v_mov_b32_e32 v69, v4
	v_mov_b32_e32 v70, v4
	v_mov_b32_e32 v71, v4
	v_mov_b32_e32 v72, v4
	v_mov_b32_e32 v73, v4
	v_mov_b32_e32 v74, v4
	v_mov_b32_e32 v75, v4
	v_mov_b32_e32 v100, v4
	v_mov_b32_e32 v101, v4
	v_mov_b32_e32 v102, v4
	v_mov_b32_e32 v103, v4
	v_mov_b32_e32 v104, v4
	v_mov_b32_e32 v105, v4
	v_mov_b32_e32 v106, v4
	v_mov_b32_e32 v107, v4
	v_mov_b32_e32 v132, v4
	v_mov_b32_e32 v133, v4
	v_mov_b32_e32 v134, v4
	v_mov_b32_e32 v135, v4
	v_mov_b32_e32 v136, v4
	v_mov_b32_e32 v137, v4
	v_mov_b32_e32 v138, v4
	v_mov_b32_e32 v139, v4
	v_mov_b32_e32 v124, v4
	v_mov_b32_e32 v125, v4
	v_mov_b32_e32 v126, v4
	v_mov_b32_e32 v127, v4
	v_mov_b32_e32 v116, v4
	v_mov_b32_e32 v117, v4
	v_mov_b32_e32 v118, v4
	v_mov_b32_e32 v119, v4
	s_waitcnt vmcnt(0)
	v_mov_b32_e32 v76, v4
	v_mov_b32_e32 v77, v4
	v_mov_b32_e32 v78, v4
	v_mov_b32_e32 v79, v4
	v_mov_b32_e32 v80, v4
	v_mov_b32_e32 v81, v4
	v_mov_b32_e32 v82, v4
	v_mov_b32_e32 v83, v4
	v_mov_b32_e32 v108, v4
	v_mov_b32_e32 v109, v4
	v_mov_b32_e32 v110, v4
	v_mov_b32_e32 v111, v4
	v_mov_b32_e32 v112, v4
	v_mov_b32_e32 v113, v4
	v_mov_b32_e32 v114, v4
	v_mov_b32_e32 v115, v4
	v_mov_b32_e32 v144, v4
	v_mov_b32_e32 v145, v4
	v_mov_b32_e32 v146, v4
	v_mov_b32_e32 v147, v4
	v_mov_b32_e32 v140, v4
	v_mov_b32_e32 v141, v4
	v_mov_b32_e32 v142, v4
	v_mov_b32_e32 v143, v4
	v_mov_b32_e32 v128, v4
	v_mov_b32_e32 v129, v4
	v_mov_b32_e32 v130, v4
	v_mov_b32_e32 v131, v4
	v_mov_b32_e32 v120, v4
	v_mov_b32_e32 v121, v4
	v_mov_b32_e32 v122, v4
	v_mov_b32_e32 v123, v4
	s_barrier

.LBB0_527:
	s_add_u32 s4, s4, 0x13600000
	v_lshrrev_b32_e32 v20, 1, v18
	s_addc_u32 s5, s5, 0
	v_and_b32_e32 v20, 24, v20
	s_lshl_b32 s7, s7, 5
	v_and_b32_e32 v19, 15, v18
	v_lshlrev_b32_e32 v21, 1, v20
	v_lshlrev_b32_e32 v18, 2, v18
	s_and_b32 s10, s7, 0x60
	s_add_i32 m0, s41, 0x18000
	v_lshl_add_u64 v[10:11], v[10:11], 0, s[22:23]
	v_lshl_or_b32 v144, s8, 6, v19
	v_lshl_or_b32 v19, v19, 6, v21
	s_lshl_b32 s8, s8, 13
	v_and_b32_e32 v18, 32, v18
	s_lshl_b32 s7, s10, 7
	global_load_lds_dwordx4 v[10:11], off
	v_lshl_add_u64 v[8:9], v[8:9], 0, s[22:23]
	s_add_i32 m0, s41, 0x1a000
	s_add_i32 s49, s41, 0x8000
	s_add_i32 s50, s41, 0xa000
	v_bitop3_b32 v21, v19, s8, v18 bitop3:0xde
	global_load_lds_dwordx4 v[8:9], off
	v_lshl_add_u64 v[4:5], v[4:5], 0, s[22:23]
	s_mov_b32 m0, s49
	s_add_u32 s8, s16, 0x40080
	global_load_lds_dwordx4 v[4:5], off
	v_lshl_add_u64 v[4:5], v[6:7], 0, s[22:23]
	s_mov_b32 m0, s50
	s_addc_u32 s9, s17, 0
	global_load_lds_dwordx4 v[4:5], off
	s_add_i32 m0, s41, 0x1c000
	v_lshl_add_u64 v[4:5], s[8:9], 0, v[2:3]
	global_load_lds_dwordx4 v[4:5], off
	v_lshl_add_u64 v[4:5], s[8:9], 0, v[0:1]
	s_add_i32 m0, s41, 0x1e000
	s_cmpk_lt_u32 s6, 0x100
	global_load_lds_dwordx4 v[4:5], off
	v_lshlrev_b32_e32 v4, 14, v16
	v_and_b32_e32 v4, 0xffff8000, v4
	v_lshl_add_u32 v4, v15, 11, v4
	v_and_b32_e32 v5, 1, v16
	v_lshl_or_b32 v4, v5, 6, v4
	v_lshl_add_u32 v136, v17, 1, v4
	v_lshlrev_b32_e32 v4, 14, v12
	v_and_b32_e32 v4, 0xffff8000, v4
	s_waitcnt vmcnt(8)
	s_barrier
	s_waitcnt vmcnt(6)
	v_lshl_add_u32 v4, v13, 11, v4
	v_and_b32_e32 v5, 1, v12
	v_lshl_or_b32 v4, v5, 6, v4
	v_readlane_b32 s8, v249, 31
	v_bitop3_b32 v145, v19, s7, v18 bitop3:0xde
	s_cselect_b64 s[6:7], -1, 0
	v_or_b32_e32 v146, s10, v20
	v_mov_b32_e32 v137, v3
	v_lshl_add_u32 v138, v14, 1, v4
	v_mov_b32_e32 v139, v3
	s_mov_b32 s51, 0
	v_add_u32_e32 v147, 0, v21
	v_readlane_b32 s52, v249, 24
	s_mov_b32 s53, s8
	s_barrier
	v_readlane_b32 s9, v249, 32
	s_waitcnt vmcnt(0)
	s_branch .LBB0_530

.LBB0_604:
	v_and_b32_e32 v193, 15, v190
	v_and_b32_e32 v20, 48, v190
	v_lshlrev_b32_e32 v21, 2, v190
	s_and_b32 s36, s21, 3
	s_lshl_b32 s14, s20, 13
	v_lshl_or_b32 v20, v193, 6, v20
	v_and_b32_e32 v21, 32, v21
	s_add_i32 m0, s38, 0x18000
	v_lshl_add_u64 v[10:11], v[10:11], 0, s[22:23]
	v_bitop3_b32 v22, v20, s14, v21 bitop3:0xde
	s_lshl_b32 s14, s36, 12
	global_load_lds_dwordx4 v[10:11], off
	v_lshl_add_u64 v[8:9], v[8:9], 0, s[22:23]
	s_add_i32 m0, s38, 0x1a000
	s_add_i32 s50, s38, 0x8000
	s_add_i32 s51, s38, 0xa000
	v_bitop3_b32 v136, v20, s14, v21 bitop3:0xde
	global_load_lds_dwordx4 v[8:9], off
	v_lshl_add_u64 v[6:7], v[6:7], 0, s[22:23]
	s_mov_b32 m0, s50
	s_add_u32 s14, s0, 0xb0080
	global_load_lds_dwordx4 v[6:7], off
	v_lshl_add_u64 v[4:5], v[4:5], 0, s[22:23]
	s_mov_b32 m0, s51
	s_addc_u32 s15, s1, 0
	global_load_lds_dwordx4 v[4:5], off
	s_add_i32 m0, s38, 0x1c000
	v_lshl_add_u64 v[4:5], s[14:15], 0, v[2:3]
	global_load_lds_dwordx4 v[4:5], off
	v_lshl_add_u64 v[4:5], s[14:15], 0, v[130:131]
	s_add_i32 m0, s38, 0x1e000
	s_add_u32 s13, s10, s13
	global_load_lds_dwordx4 v[4:5], off
	v_lshrrev_b32_e32 v5, 1, v12
	v_mul_lo_u32 v4, v14, s63
	s_mov_b32 s14, 0xb000
	s_addc_u32 s12, s11, s12
	v_mad_u64_u32 v[4:5], s[10:11], v5, s14, v[4:5]
	v_readlane_b32 s10, v249, 35
	v_or_b32_e32 v4, v4, v13
	s_add_u32 s10, s10, s13
	v_readlane_b32 s11, v249, 36
	v_add_lshl_u32 v4, v4, v15, 1
	v_mov_b32_e32 v5, v3
	s_addc_u32 s11, s11, s12
	v_lshl_add_u64 v[132:133], s[10:11], 0, v[4:5]
	v_lshrrev_b32_e32 v5, 1, v16
	v_mul_lo_u32 v4, v18, s63
	v_mad_u64_u32 v[4:5], s[12:13], v5, s14, v[4:5]
	v_or_b32_e32 v4, v4, v17
	s_waitcnt vmcnt(8)
	s_barrier
	s_waitcnt vmcnt(6)
	v_add_lshl_u32 v4, v4, v19, 1
	v_mov_b32_e32 v5, v3
	v_lshl_add_u64 v[134:135], s[10:11], 0, v[4:5]
	v_mov_b32_e32 v4, 0
	v_lshl_or_b32 v205, s20, 6, v193
	s_mov_b32 s52, -2
	s_mov_b64 s[10:11], 0
	v_add_u32_e32 v137, 0, v22
	v_mov_b32_e32 v5, v4
	v_mov_b32_e32 v6, v4
	v_mov_b32_e32 v7, v4
	v_mov_b32_e32 v8, v4
	v_mov_b32_e32 v9, v4
	v_mov_b32_e32 v10, v4
	v_mov_b32_e32 v11, v4
	v_mov_b32_e32 v20, v4
	v_mov_b32_e32 v21, v4
	v_mov_b32_e32 v22, v4
	v_mov_b32_e32 v23, v4
	v_mov_b32_e32 v24, v4
	v_mov_b32_e32 v25, v4
	v_mov_b32_e32 v26, v4
	v_mov_b32_e32 v27, v4
	v_mov_b32_e32 v36, v4
	v_mov_b32_e32 v37, v4
	v_mov_b32_e32 v38, v4
	v_mov_b32_e32 v39, v4
	v_mov_b32_e32 v40, v4
	v_mov_b32_e32 v41, v4
	v_mov_b32_e32 v42, v4
	v_mov_b32_e32 v43, v4
	v_mov_b32_e32 v52, v4
	v_mov_b32_e32 v53, v4
	v_mov_b32_e32 v54, v4
	v_mov_b32_e32 v55, v4
	v_mov_b32_e32 v56, v4
	v_mov_b32_e32 v57, v4
	v_mov_b32_e32 v58, v4
	v_mov_b32_e32 v59, v4
	v_mov_b32_e32 v12, v4
	v_mov_b32_e32 v13, v4
	v_mov_b32_e32 v14, v4
	v_mov_b32_e32 v15, v4
	v_mov_b32_e32 v16, v4
	v_mov_b32_e32 v17, v4
	v_mov_b32_e32 v18, v4
	v_mov_b32_e32 v19, v4
	v_mov_b32_e32 v28, v4
	v_mov_b32_e32 v29, v4
	v_mov_b32_e32 v30, v4
	v_mov_b32_e32 v31, v4
	v_mov_b32_e32 v32, v4
	v_mov_b32_e32 v33, v4
	v_mov_b32_e32 v34, v4
	v_mov_b32_e32 v35, v4
	v_mov_b32_e32 v44, v4
	v_mov_b32_e32 v45, v4
	v_mov_b32_e32 v46, v4
	v_mov_b32_e32 v47, v4
	v_mov_b32_e32 v48, v4
	v_mov_b32_e32 v49, v4
	v_mov_b32_e32 v50, v4
	v_mov_b32_e32 v51, v4
	v_mov_b32_e32 v60, v4
	v_mov_b32_e32 v61, v4
	v_mov_b32_e32 v62, v4
	v_mov_b32_e32 v63, v4
	v_mov_b32_e32 v64, v4
	v_mov_b32_e32 v65, v4
	v_mov_b32_e32 v66, v4
	v_mov_b32_e32 v67, v4
	v_mov_b32_e32 v68, v4
	v_mov_b32_e32 v69, v4
	v_mov_b32_e32 v70, v4
	v_mov_b32_e32 v71, v4
	v_mov_b32_e32 v72, v4
	v_mov_b32_e32 v73, v4
	v_mov_b32_e32 v74, v4
	v_mov_b32_e32 v75, v4
	v_mov_b32_e32 v84, v4
	v_mov_b32_e32 v85, v4
	v_mov_b32_e32 v86, v4
	v_mov_b32_e32 v87, v4
	v_mov_b32_e32 v88, v4
	v_mov_b32_e32 v89, v4
	v_mov_b32_e32 v90, v4
	v_mov_b32_e32 v91, v4
	v_mov_b32_e32 v100, v4
	v_mov_b32_e32 v101, v4
	v_mov_b32_e32 v102, v4
	v_mov_b32_e32 v103, v4
	v_mov_b32_e32 v104, v4
	v_mov_b32_e32 v105, v4
	v_mov_b32_e32 v106, v4
	v_mov_b32_e32 v107, v4
	v_mov_b32_e32 v116, v4
	v_mov_b32_e32 v117, v4
	v_mov_b32_e32 v118, v4
	v_mov_b32_e32 v119, v4
	v_mov_b32_e32 v120, v4
	v_mov_b32_e32 v121, v4
	v_mov_b32_e32 v122, v4
	v_mov_b32_e32 v123, v4
	v_mov_b32_e32 v76, v4
	v_mov_b32_e32 v77, v4
	v_mov_b32_e32 v78, v4
	v_mov_b32_e32 v79, v4
	v_mov_b32_e32 v80, v4
	v_mov_b32_e32 v81, v4
	v_mov_b32_e32 v82, v4
	v_mov_b32_e32 v83, v4
	v_mov_b32_e32 v92, v4
	v_mov_b32_e32 v93, v4
	v_mov_b32_e32 v94, v4
	v_mov_b32_e32 v95, v4
	v_mov_b32_e32 v96, v4
	v_mov_b32_e32 v97, v4
	v_mov_b32_e32 v98, v4
	v_mov_b32_e32 v99, v4
	v_mov_b32_e32 v108, v4
	v_mov_b32_e32 v109, v4
	v_mov_b32_e32 v110, v4
	v_mov_b32_e32 v111, v4
	v_mov_b32_e32 v112, v4
	v_mov_b32_e32 v113, v4
	v_mov_b32_e32 v114, v4
	v_mov_b32_e32 v115, v4
	v_mov_b32_e32 v124, v4
	v_mov_b32_e32 v125, v4
	v_mov_b32_e32 v126, v4
	v_mov_b32_e32 v127, v4
	v_mov_b32_e32 v144, v4
	v_mov_b32_e32 v145, v4
	v_mov_b32_e32 v146, v4
	v_mov_b32_e32 v147, v4
	s_barrier
